# FFN/pool weight transposes moved after out-proj GEMM onto non-tail workgroups (overlap with tail half-units)
# speedup vs baseline: 1.0132x; 1.0132x over previous
; #define LAS __attribute__((address_space(3)))
; #define PHASE_IDS() const int tid = fresh_tid(), lane = tid & 63, wave = __builtin_amdgcn_readfirstlane(tid >> 6), gw = bx * NWAVES + wave; (void)lane; (void)gw
; __global__ void __launch_bounds__(NTHREADS, 2) fwd_megakernel(Params p) {
;     ...
;     bf16_t* Win_t = (bf16_t*)(ws + WS_WIN); bf16_t* Wout_t = (bf16_t*)(ws + WS_WOUT); float* bg = (float*)(ws + WS_BG); bf16_t* hb0 = (bf16_t*)(ws + WS_HB0); bf16_t* xb = (bf16_t*)(ws + WS_XB); float* rss = (float*)(ws + WS_RSS);
;     bf16_t* qkv = (bf16_t*)(ws + WS_QKV); bf16_t* zb = (bf16_t*)(ws + WS_Z); float* gtarr = (float*)(ws + WS_GT);
;     bf16_t* actb = (bf16_t*)(ws + WS_ACT); bf16_t* Wup_t = (bf16_t*)(ws + WS_WUP); bf16_t* Wdn_t = (bf16_t*)(ws + WS_WDN); bf16_t* Wp_t = (bf16_t*)(ws + WS_WP);
;     ...
;     {
;         PHASE_IDS();
;         LAS float* scr = (LAS float*)(lds + wave * 16384);
;         constexpr int I_UP = 16 * 176, I_DN = 44 * 32, I_P = 4 * 8;
;         constexpr int NIT = 2 * I_UP + 2 * I_DN + 4 * I_P;
;         for (int it = gw; it < NIT; it += NGW) {
.LBB0_843:
	s_or_b64 exec, exec, s[0:1]
	v_readlane_b32 s12, v245, 19
	v_readlane_b32 s26, v245, 33
	v_readlane_b32 s27, v245, 34
	s_add_u32 s0, s26, 0xdc00000
	v_readlane_b32 s13, v245, 20
	v_readlane_b32 s14, v245, 21
	v_readlane_b32 s15, v245, 22
	v_readlane_b32 s16, v245, 23
	v_readlane_b32 s17, v245, 24
	v_readlane_b32 s18, v245, 25
	v_readlane_b32 s19, v245, 26
	v_readlane_b32 s20, v245, 27
	v_readlane_b32 s21, v245, 28
	v_readlane_b32 s22, v245, 29
	v_readlane_b32 s23, v245, 30
	v_readlane_b32 s24, v245, 31
	v_readlane_b32 s25, v245, 32
	v_writelane_b32 v245, s0, 37
	s_addc_u32 s0, s27, 0
	v_writelane_b32 v245, s0, 38
	s_add_u32 s0, s26, 0xf200000
	v_writelane_b32 v245, s0, 39
	s_addc_u32 s0, s27, 0
	v_writelane_b32 v245, s0, 40
	s_add_u32 s0, s26, 0xfd00000
	v_writelane_b32 v245, s0, 41
	s_addc_u32 s0, s27, 0
	s_waitcnt vmcnt(0)
	v_mov_b32_e32 v4, v0
	v_writelane_b32 v245, s0, 42
	s_waitcnt lgkmcnt(0)
	s_barrier
	v_writelane_b32 v246, s68, 0
	v_writelane_b32 v246, s69, 1
	v_writelane_b32 v246, s82, 2
	v_writelane_b32 v246, s83, 3

; #define LAS __attribute__((address_space(3)))
; #define PHASE_IDS() const int tid = fresh_tid(), lane = tid & 63, wave = __builtin_amdgcn_readfirstlane(tid >> 6), gw = bx * NWAVES + wave; (void)lane; (void)gw
; __global__ void __launch_bounds__(NTHREADS, 2) fwd_megakernel(Params p) {
;     ...
;         PHASE_IDS();
;         LAS float* scr = (LAS float*)(lds + wave * 16384);
;         constexpr int I_UP = 16 * 176, I_DN = 44 * 32, I_P = 4 * 8;
;         constexpr int NIT = 2 * I_UP + 2 * I_DN + 4 * I_P;
;         for (int it = gw; it < NIT; it += NGW) {
;             int r = it;
;             if (r < 2 * I_UP) { const int l = r / I_UP; r -= l * I_UP; const int kb = r / 176, nb = r % 176, n0 = 32 * nb;
;                 const int bj = n0 / DFF, rem = n0 - bj * DFF, pnn = rem >> 7, c0 = rem & 127;
;                 transpose_item(w_up + (size_t)l * D * DFF2, DFF2, D, Wup_t + (size_t)l * DFF2 * D, pnn * 256 + bj * 128 + c0, nullptr, scr, kb, n0, lane, norm_ffn + l * D); continue; }
;             r -= 2 * I_UP;
;             if (r < 2 * I_DN) { const int l = r / I_DN; r -= l * I_DN; const int kb = r / 32, nb = r % 32;
;                 transpose_item(w_down + (size_t)l * DFF * D, D, DFF, Wdn_t + (size_t)l * D * DFF, 32 * nb, nullptr, scr, kb, 32 * nb, lane); continue; }
;             r -= 2 * I_DN;
;             { const int gi = r / I_P; r -= gi * I_P; const int kb = r / 8, nb = r % 8;
;               transpose_item(pool_w + (size_t)gi * 256 * 256, 256, 256, Wp_t + (size_t)gi * 256 * 256, 32 * nb, pool_scale + gi * 256, scr, kb, 32 * nb, lane); }
;         }
.LBB0_1030:
	s_cmp_lt_u32 s94, 40
	s_cbranch_scc1 .Lxp_done
	v_writelane_b32 v246, s2, 4
	v_writelane_b32 v246, s44, 5
	v_writelane_b32 v246, s45, 6
	v_writelane_b32 v246, s14, 7
	v_writelane_b32 v246, s15, 8
	v_writelane_b32 v246, s17, 9
	v_writelane_b32 v246, s19, 10
	s_nop 1
	v_readlane_b32 s68, v246, 0
	v_readlane_b32 s69, v246, 1
	v_readlane_b32 s82, v246, 2
	v_readlane_b32 s83, v246, 3
	s_sub_i32 s99, s94, 40
	s_movk_i32 s100, 216
	s_lshl_b32 s98, s99, 3
	s_movk_i32 s101, 1728
	s_mov_b64 exec, -1
	v_mov_b32_e32 v4, v0
	s_nop 0
	v_readfirstlane_b32 s0, v4
	s_ashr_i32 s0, s0, 6
	s_add_i32 s2, s0, s98
	s_cmpk_gt_i32 s2, 0x217f
	s_cbranch_scc1 .Lxp_join
	s_lshl_b32 s1, s0, 14
	v_readlane_b32 s36, v245, 19
	s_add_i32 s3, s1, 0
	v_and_b32_e32 v5, 7, v4
	v_bfe_u32 v3, v4, 3, 3
	v_readlane_b32 s37, v245, 20
	v_bfe_u32 v1, v4, 5, 1
	v_mul_u32_u24_e32 v6, 0x420, v5
	s_cmp_lg_u64 s[36:37], 0
	v_lshlrev_b32_e32 v7, 2, v3
	s_cselect_b64 s[6:7], -1, 0
	v_add3_u32 v28, s3, v6, v7
	s_cmp_lg_u64 s[68:69], 0
	v_mul_u32_u24_e32 v6, 0x84, v1
	s_cselect_b64 s[8:9], -1, 0
	v_or_b32_e32 v6, s1, v6
	v_lshlrev_b32_e32 v4, 2, v4
	s_lshl_b32 s1, s99, 8
	s_lshl_b32 s4, s0, 5
	v_lshlrev_b32_e32 v2, 3, v5
	v_readlane_b32 s38, v245, 21
	v_readlane_b32 s39, v245, 22
	v_readlane_b32 s44, v245, 27
	v_readlane_b32 s45, v245, 28
	v_mov_b32_e32 v5, 0
	v_and_b32_e32 v4, 0x7c, v4
	s_add_i32 s18, s1, s4
	s_lshl_b32 s1, s99, 6
	s_lshl_b32 s0, s0, 3
	s_mov_b32 s5, 0
	v_or_b32_e32 v29, 8, v3
	v_or_b32_e32 v30, 16, v3
	v_or_b32_e32 v31, 24, v3
	v_add3_u32 v32, v6, v4, 0
	v_lshl_add_u64 v[6:7], s[82:83], 0, v[4:5]
	s_add_i32 s3, s2, 0xffffdf00
	s_lshl_b32 s19, s100, 8
	v_or_b32_e32 v33, 14, v1
	s_add_i32 s20, s1, s0
	s_lshl_b32 s21, s100, 6
	v_or_b32_e32 v34, 12, v1
	v_or_b32_e32 v35, 10, v1
	v_or_b32_e32 v36, 8, v1
	v_or_b32_e32 v37, 6, v1
	v_or_b32_e32 v38, 4, v1
	v_or_b32_e32 v39, 2, v1
	v_lshl_add_u64 v[8:9], s[44:45], 0, v[4:5]
	v_lshl_add_u64 v[10:11], s[38:39], 0, v[4:5]
	v_cndmask_b32_e64 v40, 0, 1, s[6:7]
	s_movk_i32 s22, 0x5800
	v_lshlrev_b32_e32 v4, 1, v2
	v_readlane_b32 s40, v245, 23
	v_readlane_b32 s41, v245, 24
	v_readlane_b32 s42, v245, 25
	v_readlane_b32 s43, v245, 26
	v_readlane_b32 s46, v245, 29
	v_readlane_b32 s47, v245, 30
	v_readlane_b32 s48, v245, 31
	v_readlane_b32 s49, v245, 32
	v_readlane_b32 s50, v245, 33
	v_readlane_b32 s51, v245, 34
	s_branch .LBB0_847

; __global__ void __launch_bounds__(NTHREADS, 2) fwd_megakernel(Params p) {
;     ...
;         for (int it = gw; it < NIT; it += NGW) {
;             int r = it;
;             if (r < 2 * I_UP) { const int l = r / I_UP; r -= l * I_UP; const int kb = r / 176, nb = r % 176, n0 = 32 * nb;
.LBB0_846:
	s_add_i32 s2, s2, s101
	s_add_i32 s3, s3, s101
	s_add_i32 s18, s18, s19
	s_add_i32 s20, s20, s21
	s_cmpk_gt_i32 s2, 0x217f
	s_cbranch_scc1 .Lxp_join

; __global__ void __launch_bounds__(NTHREADS, 2) fwd_megakernel(Params p) {
;     ...
;         for (int it = gw; it < NIT; it += NGW) {
;             int r = it;
;             if (r < 2 * I_UP) { const int l = r / I_UP; r -= l * I_UP; const int kb = r / 176, nb = r % 176, n0 = 32 * nb;
;                 const int bj = n0 / DFF, rem = n0 - bj * DFF, pnn = rem >> 7, c0 = rem & 127;
;                 transpose_item(w_up + (size_t)l * D * DFF2, DFF2, D, Wup_t + (size_t)l * DFF2 * D, pnn * 256 + bj * 128 + c0, nullptr, scr, kb, n0, lane, norm_ffn + l * D); continue; }
;             r -= 2 * I_UP;
;             if (r < 2 * I_DN) { const int l = r / I_DN; r -= l * I_DN; const int kb = r / 32, nb = r % 32;
;                 transpose_item(w_down + (size_t)l * DFF * D, D, DFF, Wdn_t + (size_t)l * D * DFF, 32 * nb, nullptr, scr, kb, 32 * nb, lane); continue; }
;             r -= 2 * I_DN;
;             { const int gi = r / I_P; r -= gi * I_P; const int kb = r / 8, nb = r % 8;
;               transpose_item(pool_w + (size_t)gi * 256 * 256, 256, 256, Wp_t + (size_t)gi * 256 * 256, 32 * nb, pool_scale + gi * 256, scr, kb, 32 * nb, lane); }
;         }
;         __syncthreads();
.Lxp_join:
	v_readlane_b32 s2, v246, 4
	v_readlane_b32 s44, v246, 5
	v_readlane_b32 s45, v246, 6
	v_readlane_b32 s14, v246, 7
	v_readlane_b32 s15, v246, 8
	v_readlane_b32 s17, v246, 9
	v_readlane_b32 s19, v246, 10

; __global__ void __launch_bounds__(NTHREADS, 2) fwd_megakernel(Params p) {
	.amdhsa_kernel _Z14fwd_megakernel6Params
		.amdhsa_group_segment_fixed_size 0
		.amdhsa_private_segment_fixed_size 0
		.amdhsa_kernarg_size 448
		.amdhsa_user_sgpr_count 2
		.amdhsa_user_sgpr_dispatch_ptr 0
		.amdhsa_user_sgpr_queue_ptr 0
		.amdhsa_user_sgpr_kernarg_segment_ptr 1
		.amdhsa_user_sgpr_dispatch_id 0
		.amdhsa_user_sgpr_kernarg_preload_length 0
		.amdhsa_user_sgpr_kernarg_preload_offset 0
		.amdhsa_user_sgpr_private_segment_size 0
		.amdhsa_uses_dynamic_stack 0
		.amdhsa_enable_private_segment 0
		.amdhsa_system_sgpr_workgroup_id_x 1
		.amdhsa_system_sgpr_workgroup_id_y 0
		.amdhsa_system_sgpr_workgroup_id_z 0
		.amdhsa_system_sgpr_workgroup_info 0
		.amdhsa_system_vgpr_workitem_id 0
		.amdhsa_next_free_vgpr 248
		.amdhsa_next_free_sgpr 102
		.amdhsa_accum_offset 248
		.amdhsa_reserve_vcc 1
		.amdhsa_float_round_mode_32 0
		.amdhsa_float_round_mode_16_64 0
		.amdhsa_float_denorm_mode_32 3
		.amdhsa_float_denorm_mode_16_64 3
		.amdhsa_dx10_clamp 1
		.amdhsa_ieee_mode 1
		.amdhsa_fp16_overflow 0
		.amdhsa_tg_split 0
		.amdhsa_exception_fp_ieee_invalid_op 0
		.amdhsa_exception_fp_denorm_src 0
		.amdhsa_exception_fp_ieee_div_zero 0
		.amdhsa_exception_fp_ieee_overflow 0
		.amdhsa_exception_fp_ieee_underflow 0
		.amdhsa_exception_fp_ieee_inexact 0
		.amdhsa_exception_int_div_zero 0
	.end_amdhsa_kernel

; __global__ void __launch_bounds__(NTHREADS, 2) fwd_megakernel(Params p) {
amdhsa.kernels:
  - .agpr_count:     0
    .args:
      - .offset:         0
        .size:           192
        .value_kind:     by_value
      - .offset:         192
        .size:           4
        .value_kind:     hidden_block_count_x
      - .offset:         196
        .size:           4
        .value_kind:     hidden_block_count_y
      - .offset:         200
        .size:           4
        .value_kind:     hidden_block_count_z
      - .offset:         204
        .size:           2
        .value_kind:     hidden_group_size_x
      - .offset:         206
        .size:           2
        .value_kind:     hidden_group_size_y
      - .offset:         208
        .size:           2
        .value_kind:     hidden_group_size_z
      - .offset:         210
        .size:           2
        .value_kind:     hidden_remainder_x
      - .offset:         212
        .size:           2
        .value_kind:     hidden_remainder_y
      - .offset:         214
        .size:           2
        .value_kind:     hidden_remainder_z
      - .offset:         232
        .size:           8
        .value_kind:     hidden_global_offset_x
      - .offset:         240
        .size:           8
        .value_kind:     hidden_global_offset_y
      - .offset:         248
        .size:           8
        .value_kind:     hidden_global_offset_z
      - .offset:         256
        .size:           2
        .value_kind:     hidden_grid_dims
      - .offset:         312
        .size:           4
        .value_kind:     hidden_dynamic_lds_size
    .group_segment_fixed_size: 0
    .kernarg_segment_align: 8
    .kernarg_segment_size: 448
    .language:       OpenCL C
    .language_version:
      - 2
      - 0
    .max_flat_workgroup_size: 512
    .name:           _Z14fwd_megakernel6Params
    .private_segment_fixed_size: 0
    .sgpr_count:     108
    .sgpr_spill_count: 192
    .symbol:         _Z14fwd_megakernel6Params.kd
    .uniform_work_group_size: 1
    .uses_dynamic_stack: false
    .vgpr_count:     248
    .vgpr_spill_count: 0
    .wavefront_size: 64
